# FoX: unit-prologue loads issued together; QK block LDS reads one slot earlier with counted waits; forget-gate bias read straight into accumulators (per-row constant cq cancels in softmax)
# speedup vs baseline: 1.0097x; 1.0097x over previous
.LBB0_287:
	s_ashr_i32 s16, s74, 6
	s_and_b32 s4, s4, 31
	s_ashr_i32 s17, s16, 31
	s_lshl_b64 s[88:89], s[16:17], 11
	s_lshl_b32 s5, s4, 13
	s_or_b32 s64, s5, 0x40000
	v_lshl_add_u64 v[6:7], s[88:89], 0, v[104:105]
	v_lshl_add_u64 v[8:9], v[6:7], 0, s[64:65]
	s_or_b32 s64, s5, 0x80000
	s_bitcmp1_b32 s74, 0
	s_cselect_b64 s[96:97], -1, 0
	s_add_u32 s72, s88, s5
	s_addc_u32 s73, s89, 0
	s_or_b32 s5, s5, 0xc0000
	v_lshl_add_u64 v[6:7], v[6:7], 0, s[64:65]
	s_add_u32 s19, s88, s5
	v_lshlrev_b64 v[8:9], 7, v[8:9]
	v_lshlrev_b64 v[6:7], 7, v[6:7]
	s_addc_u32 s52, s89, 0
	s_lshl_b32 s64, s4, 7
	v_lshl_add_u64 v[130:131], v[106:107], 0, v[8:9]
	v_lshl_add_u64 v[132:133], v[106:107], 0, v[6:7]
	v_pk_add_f32 v[2:3], v[2:3], v[4:5] op_sel_hi:[1,0]
	v_pk_add_f32 v[0:1], v[0:1], v[4:5] op_sel_hi:[1,0]
	v_lshl_add_u64 v[134:135], v[114:115], 0, s[64:65]
	s_mov_b32 s53, 0
	v_xor_b32_e32 v0, 0x80000000, v0
	v_xor_b32_e32 v1, 0x80000000, v1
	v_xor_b32_e32 v2, 0x80000000, v2
	v_xor_b32_e32 v3, 0x80000000, v3
	ds_write_b128 v140, v[0:3] offset:49920
	s_waitcnt lgkmcnt(0)
	s_barrier
	s_branch .LBB0_289

.LBB0_302:
	s_add_i32 s54, s56, s70
	v_or_b32_e32 v64, s54, v136
	v_ashrrev_i32_e32 v65, 31, v64
	v_lshl_add_u64 v[0:1], s[72:73], 0, v[64:65]
	v_lshlrev_b64 v[0:1], 7, v[0:1]
	v_lshl_add_u64 v[4:5], v[110:111], 0, v[0:1]
	global_load_dwordx4 v[0:3], v[4:5], off
	global_load_dwordx4 v[12:15], v[4:5], off offset:32
	global_load_dwordx4 v[16:19], v[4:5], off offset:64
	global_load_dwordx4 v[20:23], v[4:5], off offset:96
	s_add_i32 s4, s56, 0x100
	s_lshr_b32 s55, s4, 6
	s_add_i32 s16, s55, -1
	s_ashr_i32 s4, s54, 6
	s_lshl_b32 s64, s16, 6
	s_sub_i32 s17, s16, s4
	s_lshl_b64 s[4:5], s[64:65], 7
	v_lshl_add_u64 v[8:9], v[132:133], 0, s[4:5]
	global_load_dwordx4 v[8:11], v[8:9], off
	s_lshl_b32 s48, s56, 7
	s_mov_b32 s49, s65
	s_mov_b32 s57, 0
	s_cmp_lt_i32 s17, 2
	v_lshl_add_u64 v[24:25], v[130:131], 0, s[4:5]
	global_load_dwordx4 v[24:27], v[24:25], off
	v_lshl_add_u64 v[4:5], v[130:131], 0, s[48:49]
	v_add_co_u32_e32 v4, vcc, s11, v4
	v_lshl_add_u32 v28, v64, 2, 0
	s_nop 1
	v_addc_co_u32_e32 v5, vcc, 0, v5, vcc
	global_load_dwordx4 v[4:7], v[4:5], off
	ds_read_b32 v190, v28 offset:49920
	s_waitcnt vmcnt(6)
	ds_write_b128 v189, v[0:3] offset:60416
	s_waitcnt vmcnt(5)
	ds_write_b128 v189, v[12:15] offset:61440
	s_waitcnt vmcnt(4)
	ds_write_b128 v189, v[16:19] offset:62464
	s_waitcnt vmcnt(3)
	ds_write_b128 v189, v[20:23] offset:63488
	s_waitcnt vmcnt(1)
	ds_write_b128 v109, v[24:27] offset:33280
	s_waitcnt vmcnt(0)
	ds_write_b128 v109, v[4:7] offset:8320
	ds_write_b128 v142, v[8:11] offset:16640
	s_waitcnt lgkmcnt(0)
	s_barrier
	s_cbranch_scc1 .LBB0_314
	s_add_i32 s62, s17, -1
	s_add_i32 s4, s56, 64
	s_mov_b32 s63, 0

.LBB0_314:
	s_cmp_lt_i32 s17, 1
	s_mov_b64 s[4:5], -1
	s_cbranch_scc0 .LBB0_316
	v_lshl_add_u32 v16, s64, 2, v183
	ds_read_b128 v[32:35], v189 offset:60416
	ds_read_b128 v[0:3], v16 offset:49920
	ds_read_b128 v[4:7], v16 offset:49952
	ds_read_b128 v[8:11], v16 offset:49984
	ds_read_b128 v[12:15], v16 offset:50016
	ds_read_b128 v[36:39], v16 offset:50048
	ds_read_b128 v[40:43], v16 offset:50080
	ds_read_b128 v[44:47], v16 offset:50112
	ds_read_b128 v[48:51], v16 offset:50144
	s_waitcnt lgkmcnt(7)
	v_mov_b32_e32 v19, v3
	v_mov_b32_e32 v18, v2
	v_mov_b32_e32 v17, v1
	v_mov_b32_e32 v16, v0
	ds_read_b128 v[0:3], v175 offset:33280
	s_waitcnt lgkmcnt(6)
	v_mov_b32_e32 v27, v11
	v_mov_b32_e32 v26, v10
	v_mov_b32_e32 v25, v9
	v_mov_b32_e32 v24, v8
	s_waitcnt lgkmcnt(2)
	v_mov_b32_e32 v11, v47
	v_mov_b32_e32 v10, v46
	v_mov_b32_e32 v9, v45
	v_mov_b32_e32 v8, v44
	ds_read_b128 v[44:47], v175 offset:33792
	v_mov_b32_e32 v31, v15
	v_mov_b32_e32 v30, v14
	v_mov_b32_e32 v29, v13
	v_mov_b32_e32 v28, v12
	v_mov_b32_e32 v23, v7
	v_mov_b32_e32 v22, v6
	v_mov_b32_e32 v21, v5
	v_mov_b32_e32 v20, v4
	s_waitcnt lgkmcnt(2)
	v_mov_b32_e32 v15, v51
	v_mov_b32_e32 v14, v50
	s_waitcnt lgkmcnt(1)
	v_mfma_f32_32x32x16_bf16 v[16:31], v[0:3], v[32:35], v[16:31]
	v_mov_b32_e32 v13, v49
	v_mov_b32_e32 v12, v48
	v_mov_b32_e32 v7, v43
	v_mov_b32_e32 v6, v42
	v_mov_b32_e32 v5, v41
	v_mov_b32_e32 v4, v40
	v_mov_b32_e32 v3, v39
	v_mov_b32_e32 v2, v38
	v_mov_b32_e32 v1, v37
	v_mov_b32_e32 v0, v36
	s_mov_b64 s[4:5], 0
	s_waitcnt lgkmcnt(0)
	v_mfma_f32_32x32x16_bf16 v[0:15], v[44:47], v[32:35], v[0:15]
	ds_read_b128 v[32:35], v175 offset:35360
	ds_read_b128 v[36:39], v189 offset:61440
	s_waitcnt lgkmcnt(0)
	v_mfma_f32_32x32x16_bf16 v[16:31], v[32:35], v[36:39], v[16:31]
	ds_read_b128 v[32:35], v175 offset:35872
	s_waitcnt lgkmcnt(0)
	v_mfma_f32_32x32x16_bf16 v[0:15], v[32:35], v[36:39], v[0:15]
	ds_read_b128 v[32:35], v175 offset:37440
	ds_read_b128 v[36:39], v189 offset:62464
	s_waitcnt lgkmcnt(0)
	v_mfma_f32_32x32x16_bf16 v[16:31], v[32:35], v[36:39], v[16:31]
	ds_read_b128 v[32:35], v175 offset:37952
	s_waitcnt lgkmcnt(0)
	v_mfma_f32_32x32x16_bf16 v[0:15], v[32:35], v[36:39], v[0:15]
	ds_read_b128 v[32:35], v175 offset:39520
	ds_read_b128 v[36:39], v189 offset:63488
	s_waitcnt lgkmcnt(0)
	v_mfma_f32_32x32x16_bf16 v[16:31], v[32:35], v[36:39], v[16:31]
	ds_read_b128 v[32:35], v175 offset:40032
	s_waitcnt lgkmcnt(0)
	v_mfma_f32_32x32x16_bf16 v[0:15], v[32:35], v[36:39], v[0:15]

.LBB0_321:
	v_lshl_add_u32 v16, s63, 8, v183
	ds_read_b128 v[32:35], v189 offset:60416
	ds_read_b128 v[0:3], v16 offset:49664
	ds_read_b128 v[4:7], v16 offset:49696
	ds_read_b128 v[8:11], v16 offset:49728
	ds_read_b128 v[12:15], v16 offset:49760
	ds_read_b128 v[36:39], v16 offset:49792
	ds_read_b128 v[40:43], v16 offset:49824
	ds_read_b128 v[44:47], v16 offset:49856
	ds_read_b128 v[48:51], v16 offset:49888
	s_bitcmp1_b32 s17, 0
	s_cselect_b32 s62, 0x2080, 0
	s_waitcnt lgkmcnt(4)
	v_mov_b32_e32 v30, v14
	v_mov_b32_e32 v19, v3
	s_waitcnt lgkmcnt(0)
	v_mov_b32_e32 v14, v50
	v_add_u32_e32 v50, s62, v175
	v_mov_b32_e32 v18, v2
	v_mov_b32_e32 v17, v1
	v_mov_b32_e32 v16, v0
	ds_read_b128 v[0:3], v50
	v_mov_b32_e32 v27, v11
	v_mov_b32_e32 v26, v10
	v_mov_b32_e32 v25, v9
	v_mov_b32_e32 v24, v8
	v_mov_b32_e32 v11, v47
	v_mov_b32_e32 v10, v46
	v_mov_b32_e32 v9, v45
	v_mov_b32_e32 v8, v44
	ds_read_b128 v[44:47], v50 offset:512
	v_mov_b32_e32 v31, v15
	v_mov_b32_e32 v29, v13
	v_mov_b32_e32 v28, v12
	v_mov_b32_e32 v23, v7
	v_mov_b32_e32 v22, v6
	v_mov_b32_e32 v21, v5
	v_mov_b32_e32 v20, v4
	v_mov_b32_e32 v15, v51
	v_mov_b32_e32 v13, v49
	s_waitcnt lgkmcnt(1)
	v_mfma_f32_32x32x16_bf16 v[16:31], v[0:3], v[32:35], v[16:31]
	v_mov_b32_e32 v12, v48
	v_mov_b32_e32 v7, v43
	v_mov_b32_e32 v6, v42
	v_mov_b32_e32 v5, v41
	v_mov_b32_e32 v4, v40
	v_mov_b32_e32 v3, v39
	v_mov_b32_e32 v2, v38
	v_mov_b32_e32 v1, v37
	v_mov_b32_e32 v0, v36
	s_andn2_b64 vcc, exec, s[4:5]
	s_waitcnt lgkmcnt(0)
	v_mfma_f32_32x32x16_bf16 v[0:15], v[44:47], v[32:35], v[0:15]
	ds_read_b128 v[32:35], v50 offset:2080
	ds_read_b128 v[36:39], v189 offset:61440
	s_waitcnt lgkmcnt(0)
	v_mfma_f32_32x32x16_bf16 v[16:31], v[32:35], v[36:39], v[16:31]
	ds_read_b128 v[32:35], v50 offset:2592
	s_waitcnt lgkmcnt(0)
	v_mfma_f32_32x32x16_bf16 v[0:15], v[32:35], v[36:39], v[0:15]
	ds_read_b128 v[32:35], v50 offset:4160
	ds_read_b128 v[36:39], v189 offset:62464
	s_waitcnt lgkmcnt(0)
	v_mfma_f32_32x32x16_bf16 v[16:31], v[32:35], v[36:39], v[16:31]
	ds_read_b128 v[32:35], v50 offset:4672
	s_waitcnt lgkmcnt(0)
	v_mfma_f32_32x32x16_bf16 v[0:15], v[32:35], v[36:39], v[0:15]
	ds_read_b128 v[32:35], v50 offset:6240
	ds_read_b128 v[36:39], v189 offset:63488
	s_waitcnt lgkmcnt(0)
	v_mfma_f32_32x32x16_bf16 v[16:31], v[32:35], v[36:39], v[16:31]
	ds_read_b128 v[32:35], v50 offset:6752
	s_waitcnt lgkmcnt(0)
	v_mfma_f32_32x32x16_bf16 v[0:15], v[32:35], v[36:39], v[0:15]
	s_cbranch_vccnz .LBB0_323
	v_add_u32_e32 v32, s62, v142
	s_waitcnt vmcnt(0)
	ds_write_b128 v32, v[100:103] offset:16640

.LBB0_331:
	v_lshl_add_u32 v65, s16, 8, v183
	ds_read_b128 v[32:35], v65 offset:49728
	ds_read_b128 v[36:39], v65 offset:49760
	ds_read_b128 v[40:43], v65 offset:49664
	ds_read_b128 v[44:47], v65 offset:49696
	s_bitcmp1_b32 s57, 0
	s_cselect_b32 s62, 0x2080, 0
	s_bitcmp1_b32 s17, 0
	s_cselect_b64 s[90:91], -1, 0
	s_and_b64 vcc, s[90:91], exec
	s_cselect_b32 s16, 0x2080, 0
	s_waitcnt lgkmcnt(2)
	v_mov_b32_e32 v63, v39
	v_mov_b32_e32 v62, v38
	v_mov_b32_e32 v61, v37
	v_mov_b32_e32 v60, v36
	v_mov_b32_e32 v59, v35
	v_mov_b32_e32 v58, v34
	v_mov_b32_e32 v57, v33
	v_mov_b32_e32 v56, v32
	s_waitcnt lgkmcnt(0)
	v_mov_b32_e32 v55, v47
	v_mov_b32_e32 v54, v46
	v_mov_b32_e32 v53, v45
	v_mov_b32_e32 v52, v44
	v_mov_b32_e32 v51, v43
	v_mov_b32_e32 v50, v42
	v_mov_b32_e32 v49, v41
	v_mov_b32_e32 v48, v40
	ds_read_b128 v[32:35], v65 offset:49792
	ds_read_b128 v[36:39], v65 offset:49824
	ds_read_b128 v[40:43], v65 offset:49856
	ds_read_b128 v[44:47], v65 offset:49888
	v_add_u32_e32 v65, s62, v144
	ds_read_b128 v[66:69], v65
	ds_read_b128 v[70:73], v189 offset:60416
	s_waitcnt lgkmcnt(4)
	v_mov_b32_e32 v39, v39
	s_waitcnt lgkmcnt(3)
	v_mov_b32_e32 v43, v43
	s_waitcnt lgkmcnt(2)
	v_mov_b32_e32 v47, v47
	v_mov_b32_e32 v46, v46
	v_mov_b32_e32 v45, v45
	v_mov_b32_e32 v44, v44
	v_mov_b32_e32 v42, v42
	v_mov_b32_e32 v41, v41
	v_mov_b32_e32 v40, v40
	v_mov_b32_e32 v38, v38
	v_mov_b32_e32 v37, v37
	v_mov_b32_e32 v36, v36
	v_mov_b32_e32 v35, v35
	v_mov_b32_e32 v34, v34
	v_mov_b32_e32 v33, v33
	v_mov_b32_e32 v32, v32
	v_or_b32_e32 v78, s63, v145
	s_waitcnt lgkmcnt(0)
	v_mfma_f32_32x32x16_bf16 v[48:63], v[66:69], v[70:73], v[48:63]
	v_cmp_le_i32_e32 vcc, v78, v64
	ds_read_b128 v[74:77], v65 offset:512
	s_nop 0
	v_cndmask_b32_e32 v79, v235, v16, vcc
	v_cmp_lt_i32_e32 vcc, v78, v64
	s_nop 1
	v_cndmask_b32_e32 v80, v235, v17, vcc
	v_or_b32_e32 v17, 2, v78
	v_cmp_le_i32_e32 vcc, v17, v64
	v_or_b32_e32 v17, 3, v78
	v_max3_f32 v16, v79, s94, v80
	v_cndmask_b32_e32 v81, v235, v18, vcc
	v_cmp_le_i32_e32 vcc, v17, v64
	s_nop 1
	v_cndmask_b32_e32 v82, v235, v19, vcc
	v_max3_f32 v83, v16, v81, v82
	s_waitcnt lgkmcnt(0)
	v_mfma_f32_32x32x16_bf16 v[32:47], v[74:77], v[70:73], v[32:47]
	v_or_b32_e32 v70, 8, v78
	v_cmp_le_i32_e32 vcc, v70, v64
	ds_read_b128 v[16:19], v65 offset:2080
	ds_read_b128 v[66:69], v189 offset:61440
	v_cndmask_b32_e32 v72, v235, v20, vcc
	v_or_b32_e32 v20, 9, v78
	v_cmp_le_i32_e32 vcc, v20, v64
	s_nop 1
	v_cndmask_b32_e32 v73, v235, v21, vcc
	v_or_b32_e32 v21, 10, v78
	v_cmp_le_i32_e32 vcc, v21, v64
	v_or_b32_e32 v21, 11, v78
	v_max3_f32 v20, v83, v72, v73
	v_cndmask_b32_e32 v74, v235, v22, vcc
	v_cmp_le_i32_e32 vcc, v21, v64
	s_nop 1
	v_cndmask_b32_e32 v75, v235, v23, vcc
	v_max3_f32 v70, v20, v74, v75
	s_waitcnt lgkmcnt(0)
	v_mfma_f32_32x32x16_bf16 v[48:63], v[16:19], v[66:69], v[48:63]
	v_or_b32_e32 v16, 16, v78
	v_cmp_le_i32_e32 vcc, v16, v64
	v_or_b32_e32 v16, 17, v78
	ds_read_b128 v[20:23], v65 offset:2592
	v_cndmask_b32_e32 v76, v235, v24, vcc
	v_cmp_le_i32_e32 vcc, v16, v64
	v_or_b32_e32 v17, 18, v78
	s_nop 0
	v_cndmask_b32_e32 v77, v235, v25, vcc
	v_cmp_le_i32_e32 vcc, v17, v64
	v_or_b32_e32 v17, 19, v78
	v_max3_f32 v16, v70, v76, v77
	v_cndmask_b32_e32 v83, v235, v26, vcc
	v_cmp_le_i32_e32 vcc, v17, v64
	s_nop 1
	v_cndmask_b32_e32 v84, v235, v27, vcc
	v_max3_f32 v70, v16, v83, v84
	s_waitcnt lgkmcnt(0)
	v_mfma_f32_32x32x16_bf16 v[32:47], v[20:23], v[66:69], v[32:47]
	v_or_b32_e32 v20, 24, v78
	v_cmp_le_i32_e32 vcc, v20, v64
	v_or_b32_e32 v20, 25, v78
	ds_read_b128 v[16:19], v65 offset:4160
	ds_read_b128 v[24:27], v189 offset:62464
	v_cndmask_b32_e32 v28, v235, v28, vcc
	v_cmp_le_i32_e32 vcc, v20, v64
	v_or_b32_e32 v21, 26, v78
	s_nop 0
	v_cndmask_b32_e32 v29, v235, v29, vcc
	v_cmp_le_i32_e32 vcc, v21, v64
	v_or_b32_e32 v21, 27, v78
	v_max3_f32 v20, v70, v28, v29
	v_cndmask_b32_e32 v30, v235, v30, vcc
	v_cmp_le_i32_e32 vcc, v21, v64
	s_nop 1
	v_cndmask_b32_e32 v31, v235, v31, vcc
	v_max3_f32 v66, v20, v30, v31
	s_waitcnt lgkmcnt(0)
	v_mfma_f32_32x32x16_bf16 v[48:63], v[16:19], v[24:27], v[48:63]
	v_or_b32_e32 v16, 32, v78
	v_cmp_le_i32_e32 vcc, v16, v64
	ds_read_b128 v[20:23], v65 offset:4672
	s_nop 0
	v_cndmask_b32_e32 v67, v235, v0, vcc
	v_or_b32_e32 v0, 33, v78
	v_cmp_le_i32_e32 vcc, v0, v64
	s_nop 1
	v_cndmask_b32_e32 v85, v235, v1, vcc
	v_or_b32_e32 v1, 34, v78
	v_cmp_le_i32_e32 vcc, v1, v64
	v_or_b32_e32 v1, 35, v78
	v_max3_f32 v0, v66, v67, v85
	v_cndmask_b32_e32 v66, v235, v2, vcc
	v_cmp_le_i32_e32 vcc, v1, v64
	s_nop 1
	v_cndmask_b32_e32 v87, v235, v3, vcc
	v_max3_f32 v68, v0, v66, v87
	s_waitcnt lgkmcnt(0)
	v_mfma_f32_32x32x16_bf16 v[32:47], v[20:23], v[24:27], v[32:47]
	v_or_b32_e32 v20, 40, v78
	v_cmp_le_i32_e32 vcc, v20, v64
	ds_read_b128 v[0:3], v65 offset:6240
	ds_read_b128 v[16:19], v189 offset:63488
	v_cndmask_b32_e32 v20, v235, v4, vcc
	v_or_b32_e32 v4, 41, v78
	v_cmp_le_i32_e32 vcc, v4, v64
	s_nop 1
	v_cndmask_b32_e32 v21, v235, v5, vcc
	v_or_b32_e32 v5, 42, v78
	v_cmp_le_i32_e32 vcc, v5, v64
	v_or_b32_e32 v5, 43, v78
	v_max3_f32 v4, v68, v20, v21
	v_cndmask_b32_e32 v22, v235, v6, vcc
	v_cmp_le_i32_e32 vcc, v5, v64
	s_nop 1
	v_cndmask_b32_e32 v24, v235, v7, vcc
	v_max3_f32 v23, v4, v22, v24
	v_or_b32_e32 v25, 48, v78
	s_waitcnt lgkmcnt(0)
	v_mfma_f32_32x32x16_bf16 v[48:63], v[0:3], v[16:19], v[48:63]
	v_cmp_le_i32_e32 vcc, v25, v64
	ds_read_b128 v[4:7], v65 offset:6752
	v_or_b32_e32 v1, 50, v78
	v_cndmask_b32_e32 v25, v235, v8, vcc
	v_or_b32_e32 v8, 49, v78
	v_cmp_le_i32_e32 vcc, v8, v64
	s_nop 1
	v_cndmask_b32_e32 v93, v235, v9, vcc
	v_cmp_le_i32_e32 vcc, v1, v64
	v_or_b32_e32 v1, 51, v78
	v_max3_f32 v0, v23, v25, v93
	v_cndmask_b32_e32 v94, v235, v10, vcc
	v_cmp_le_i32_e32 vcc, v1, v64
	s_nop 1
	v_cndmask_b32_e32 v95, v235, v11, vcc
	v_max3_f32 v0, v0, v94, v95
	s_waitcnt lgkmcnt(0)
	v_mfma_f32_32x32x16_bf16 v[32:47], v[4:7], v[16:19], v[32:47]
	v_or_b32_e32 v1, 56, v78
	v_cmp_le_i32_e32 vcc, v1, v64
	v_or_b32_e32 v1, 57, v78
	s_nop 0
	v_cndmask_b32_e32 v191, v235, v12, vcc
	v_cmp_le_i32_e32 vcc, v1, v64
	v_or_b32_e32 v1, 58, v78
	s_nop 0
	v_cndmask_b32_e32 v197, v235, v13, vcc
	v_cmp_le_i32_e32 vcc, v1, v64
	v_or_b32_e32 v1, 59, v78
	v_max3_f32 v0, v0, v191, v197
	v_cndmask_b32_e32 v204, v235, v14, vcc
	v_cmp_le_i32_e32 vcc, v1, v64
	s_nop 1
	v_cndmask_b32_e32 v206, v235, v15, vcc
	v_max3_f32 v0, v0, v204, v206
	v_mov_b32_e32 v1, v0
	v_mov_b32_e32 v2, v0
	s_nop 1
	v_permlane32_swap_b32_e32 v1, v2
	v_cndmask_b32_e64 v1, v1, v2, s[36:37]
	v_max_f32_e32 v1, v1, v1
	v_max_f32_e32 v196, v0, v1
	v_sub_f32_e32 v0, v79, v196
	v_exp_f32_e32 v68, v0
	v_sub_f32_e32 v0, v80, v196
	v_exp_f32_e32 v69, v0
	v_sub_f32_e32 v0, v81, v196
	v_exp_f32_e32 v70, v0
	v_sub_f32_e32 v0, v82, v196
	v_exp_f32_e32 v71, v0
	v_sub_f32_e32 v0, v72, v196
	v_exp_f32_e32 v72, v0
	v_sub_f32_e32 v0, v73, v196
	v_exp_f32_e32 v73, v0
	v_sub_f32_e32 v0, v74, v196
	v_exp_f32_e32 v74, v0
	v_sub_f32_e32 v0, v75, v196
	v_exp_f32_e32 v75, v0
	v_sub_f32_e32 v0, v76, v196
	v_exp_f32_e32 v76, v0
	v_sub_f32_e32 v0, v77, v196
	v_exp_f32_e32 v77, v0
	v_sub_f32_e32 v0, v83, v196
	v_exp_f32_e32 v78, v0
	v_sub_f32_e32 v0, v84, v196
	v_exp_f32_e32 v79, v0
	v_sub_f32_e32 v0, v28, v196
	v_exp_f32_e32 v80, v0
	v_sub_f32_e32 v0, v29, v196
	v_exp_f32_e32 v81, v0
	v_sub_f32_e32 v0, v30, v196
	v_exp_f32_e32 v82, v0
	v_sub_f32_e32 v0, v31, v196
	v_exp_f32_e32 v83, v0
	v_sub_f32_e32 v0, v67, v196
	v_exp_f32_e32 v84, v0
	v_sub_f32_e32 v0, v85, v196
	v_exp_f32_e32 v85, v0
	v_sub_f32_e32 v0, v66, v196
	v_exp_f32_e32 v86, v0
	v_sub_f32_e32 v0, v87, v196
	v_add_u32_e32 v207, s16, v149
	v_cvt_pk_bf16_f32 v16, v68, v69
	v_cvt_pk_bf16_f32 v17, v70, v71
	v_cvt_pk_bf16_f32 v18, v72, v73
	v_cvt_pk_bf16_f32 v19, v74, v75
	v_exp_f32_e32 v87, v0
	ds_read_b64_tr_b16 v[0:1], v207 offset:16640
	ds_read_b64_tr_b16 v[2:3], v207 offset:17152
	v_sub_f32_e32 v4, v20, v196
	v_exp_f32_e32 v88, v4
	v_sub_f32_e32 v4, v21, v196
	v_exp_f32_e32 v89, v4
	s_waitcnt lgkmcnt(0)
	v_mfma_f32_32x32x16_bf16 v[0:15], v[16:19], v[0:3], 0
	v_sub_f32_e32 v26, v22, v196
	ds_read_b64_tr_b16 v[20:21], v207 offset:20800
	ds_read_b64_tr_b16 v[22:23], v207 offset:21312
	v_cvt_pk_bf16_f32 v64, v76, v77
	v_cvt_pk_bf16_f32 v65, v78, v79
	v_cvt_pk_bf16_f32 v66, v80, v81
	v_cvt_pk_bf16_f32 v67, v82, v83
	ds_read_b64_tr_b16 v[198:199], v207 offset:17664
	ds_read_b64_tr_b16 v[200:201], v207 offset:18176
	v_sub_f32_e32 v24, v24, v196
	v_exp_f32_e32 v90, v26
	v_exp_f32_e32 v91, v24
	v_sub_f32_e32 v92, v25, v196
	s_waitcnt lgkmcnt(2)
	v_mfma_f32_32x32x16_bf16 v[16:31], v[16:19], v[20:23], 0
	v_cvt_pk_bf16_f32 v192, v84, v85
	v_cvt_pk_bf16_f32 v193, v86, v87
	v_cvt_pk_bf16_f32 v194, v88, v89
	v_cvt_pk_bf16_f32 v195, v90, v91
	v_sub_f32_e32 v93, v93, v196
	v_sub_f32_e32 v94, v94, v196
	v_sub_f32_e32 v95, v95, v196
	s_waitcnt lgkmcnt(0)
	v_mfma_f32_32x32x16_bf16 v[0:15], v[64:67], v[198:201], v[0:15]
	ds_read_b64_tr_b16 v[200:201], v207 offset:21824
	ds_read_b64_tr_b16 v[202:203], v207 offset:22336
	v_exp_f32_e32 v92, v92
	v_exp_f32_e32 v93, v93
	v_exp_f32_e32 v94, v94
	v_exp_f32_e32 v95, v95
	s_andn2_b64 vcc, exec, s[48:49]
	v_cvt_pk_bf16_f32 v198, v92, v93
	s_waitcnt lgkmcnt(0)
	v_mfma_f32_32x32x16_bf16 v[16:31], v[64:67], v[200:203], v[16:31]
	ds_read_b64_tr_b16 v[200:201], v207 offset:18688
	ds_read_b64_tr_b16 v[202:203], v207 offset:19200
	v_sub_f32_e32 v64, v191, v196
	v_sub_f32_e32 v65, v197, v196
	v_sub_f32_e32 v66, v204, v196
	v_sub_f32_e32 v67, v206, v196
	v_exp_f32_e32 v64, v64
	v_exp_f32_e32 v65, v65
	s_waitcnt lgkmcnt(0)
	v_mfma_f32_32x32x16_bf16 v[0:15], v[192:195], v[200:203], v[0:15]
	ds_read_b64_tr_b16 v[202:203], v207 offset:22848
	ds_read_b64_tr_b16 v[204:205], v207 offset:23360
	v_exp_f32_e32 v66, v66
	v_exp_f32_e32 v67, v67
	v_cvt_pk_bf16_f32 v199, v94, v95
	v_cvt_pk_bf16_f32 v200, v64, v65
	v_cvt_pk_bf16_f32 v201, v66, v67
	s_waitcnt lgkmcnt(0)
	v_mfma_f32_32x32x16_bf16 v[16:31], v[192:195], v[202:205], v[16:31]
	ds_read_b64_tr_b16 v[192:193], v207 offset:19712
	ds_read_b64_tr_b16 v[194:195], v207 offset:20224
	s_waitcnt lgkmcnt(0)
	v_mfma_f32_32x32x16_bf16 v[0:15], v[198:201], v[192:195], v[0:15]
	ds_read_b64_tr_b16 v[192:193], v207 offset:23872
	ds_read_b64_tr_b16 v[194:195], v207 offset:24384
	s_waitcnt lgkmcnt(0)
	v_mfma_f32_32x32x16_bf16 v[16:31], v[198:201], v[192:195], v[16:31]
	s_cbranch_vccnz .LBB0_333
	v_add_u32_e32 v191, s62, v142
	s_waitcnt vmcnt(0)
	ds_write_b128 v191, v[100:103] offset:16640

.LBB0_339:
	ds_read_b128 v[92:95], v192 offset:352
	ds_read_b128 v[88:91], v192 offset:320
	ds_read_b128 v[80:83], v192 offset:256
	ds_read_b128 v[84:87], v192 offset:288
	ds_read_b128 v[198:201], v193
	ds_read_b128 v[202:205], v189 offset:60416
	ds_read_b128 v[64:67], v192 offset:384
	ds_read_b128 v[68:71], v192 offset:416
	ds_read_b128 v[72:75], v192 offset:448
	ds_read_b128 v[76:79], v192 offset:480
	ds_read_b128 v[206:209], v193 offset:512
	ds_read_b128 v[210:213], v189 offset:61440
	s_waitcnt lgkmcnt(6)
	v_mfma_f32_32x32x16_bf16 v[80:95], v[198:201], v[202:205], v[80:95]
	ds_read_b128 v[198:201], v193 offset:2080
	v_max3_f32 v197, v48, s94, v49
	v_max3_f32 v197, v197, v50, v51
	s_waitcnt lgkmcnt(2)
	v_mfma_f32_32x32x16_bf16 v[64:79], v[206:209], v[202:205], v[64:79]
	ds_read_b128 v[202:205], v193 offset:2592
	ds_read_b128 v[206:209], v189 offset:62464
	v_max3_f32 v197, v197, v52, v53
	v_max3_f32 v197, v197, v54, v55
	s_waitcnt lgkmcnt(2)
	v_mfma_f32_32x32x16_bf16 v[80:95], v[198:201], v[210:213], v[80:95]
	ds_read_b128 v[198:201], v193 offset:4160
	v_max3_f32 v197, v197, v56, v57
	v_max3_f32 v197, v197, v58, v59
	s_waitcnt lgkmcnt(2)
	v_mfma_f32_32x32x16_bf16 v[64:79], v[202:205], v[210:213], v[64:79]
	ds_read_b128 v[202:205], v193 offset:4672
	ds_read_b128 v[210:213], v189 offset:63488
	v_max3_f32 v197, v197, v60, v61
	v_max3_f32 v197, v197, v62, v63
	s_waitcnt lgkmcnt(2)
	v_mfma_f32_32x32x16_bf16 v[80:95], v[198:201], v[206:209], v[80:95]
	ds_read_b128 v[198:201], v193 offset:6240
	v_max3_f32 v197, v197, v32, v33
	v_max3_f32 v197, v197, v34, v35
	s_waitcnt lgkmcnt(2)
	v_mfma_f32_32x32x16_bf16 v[64:79], v[202:205], v[206:209], v[64:79]
	ds_read_b128 v[202:205], v193 offset:6752
	v_max3_f32 v197, v197, v36, v37
	v_max3_f32 v197, v197, v38, v39
	s_waitcnt lgkmcnt(1)
	v_mfma_f32_32x32x16_bf16 v[80:95], v[198:201], v[210:213], v[80:95]
	v_max3_f32 v197, v197, v40, v41
	v_max3_f32 v197, v197, v42, v43
	s_waitcnt lgkmcnt(0)
	v_mfma_f32_32x32x16_bf16 v[64:79], v[202:205], v[210:213], v[64:79]
	v_max3_f32 v197, v197, v44, v45
	v_max3_f32 v197, v197, v46, v47
	v_mov_b32_e32 v198, v197
	v_mov_b32_e32 v199, v197
	s_nop 1
	v_permlane32_swap_b32_e32 v198, v199
	v_cndmask_b32_e64 v198, v198, v199, s[36:37]
	v_max_f32_e32 v198, v198, v198
	v_max_f32_e32 v197, v197, v198
	v_add_f32_e32 v198, 0x40c00000, v196
	v_cmp_gt_f32_e32 vcc, v197, v198
	s_nop 1
	v_cndmask_b32_e32 v236, v196, v197, vcc
	v_sub_f32_e32 v197, v196, v236
	v_exp_f32_e32 v197, v197
	v_cmp_neq_f32_e32 vcc, v236, v196
	s_cbranch_vccz .LBB0_343
	s_and_saveexec_b64 s[48:49], s[36:37]
	ds_write_b32 v176, v197 offset:58112
	s_or_b64 exec, exec, s[48:49]
	v_add_u32_e32 v196, s75, v108
	ds_read_b128 v[198:201], v196 offset:58208
	ds_read_b128 v[202:205], v196 offset:58176
	ds_read_b128 v[206:209], v196 offset:58144
	ds_read_b128 v[210:213], v196 offset:58112
	s_waitcnt lgkmcnt(3)
	v_pk_mul_f32 v[28:29], v[28:29], v[198:199]
	s_waitcnt lgkmcnt(2)
	v_pk_mul_f32 v[24:25], v[24:25], v[202:203]
	s_waitcnt lgkmcnt(1)
	v_pk_mul_f32 v[20:21], v[20:21], v[206:207]
	s_waitcnt lgkmcnt(0)
	v_pk_mul_f32 v[16:17], v[16:17], v[210:211]
	v_pk_mul_f32 v[12:13], v[12:13], v[198:199]
	v_pk_mul_f32 v[8:9], v[8:9], v[202:203]
	v_pk_mul_f32 v[4:5], v[4:5], v[206:207]
	v_pk_mul_f32 v[30:31], v[30:31], v[200:201]
	v_pk_mul_f32 v[26:27], v[26:27], v[204:205]
	v_pk_mul_f32 v[22:23], v[22:23], v[208:209]
	v_pk_mul_f32 v[18:19], v[18:19], v[212:213]
	v_pk_mul_f32 v[14:15], v[14:15], v[200:201]
	v_pk_mul_f32 v[10:11], v[10:11], v[204:205]
	v_pk_mul_f32 v[6:7], v[6:7], v[208:209]
	v_pk_mul_f32 v[2:3], v[2:3], v[212:213]
	v_pk_mul_f32 v[0:1], v[0:1], v[210:211]

.LBB0_349:
	ds_read_b128 v[60:63], v192 offset:96
	ds_read_b128 v[56:59], v192 offset:64
	ds_read_b128 v[48:51], v192
	ds_read_b128 v[52:55], v192 offset:32
	v_add_u32_e32 v196, s64, v144
	ds_read_b128 v[238:241], v196
	ds_read_b128 v[242:245], v189 offset:60416
	ds_read_b128 v[32:35], v192 offset:128
	ds_read_b128 v[36:39], v192 offset:160
	ds_read_b128 v[40:43], v192 offset:192
	ds_read_b128 v[44:47], v192 offset:224
	ds_read_b128 v[246:249], v196 offset:512
	ds_read_b128 v[250:253], v189 offset:61440
	s_waitcnt lgkmcnt(6)
	v_mfma_f32_32x32x16_bf16 v[48:63], v[238:241], v[242:245], v[48:63]
	ds_read_b128 v[238:241], v196 offset:2080
	v_max3_f32 v237, v80, s94, v81
	v_max3_f32 v237, v237, v82, v83
	s_waitcnt lgkmcnt(2)
	v_mfma_f32_32x32x16_bf16 v[32:47], v[246:249], v[242:245], v[32:47]
	ds_read_b128 v[242:245], v196 offset:2592
	ds_read_b128 v[246:249], v189 offset:62464
	v_max3_f32 v237, v237, v84, v85
	v_max3_f32 v237, v237, v86, v87
	s_waitcnt lgkmcnt(2)
	v_mfma_f32_32x32x16_bf16 v[48:63], v[238:241], v[250:253], v[48:63]
	ds_read_b128 v[238:241], v196 offset:4160
	v_max3_f32 v237, v237, v88, v89
	v_max3_f32 v237, v237, v90, v91
	s_waitcnt lgkmcnt(2)
	v_mfma_f32_32x32x16_bf16 v[32:47], v[242:245], v[250:253], v[32:47]
	ds_read_b128 v[242:245], v196 offset:4672
	ds_read_b128 v[250:253], v189 offset:63488
	v_max3_f32 v237, v237, v92, v93
	v_max3_f32 v237, v237, v94, v95
	s_waitcnt lgkmcnt(2)
	v_mfma_f32_32x32x16_bf16 v[48:63], v[238:241], v[246:249], v[48:63]
	ds_read_b128 v[238:241], v196 offset:6240
	v_max3_f32 v237, v237, v64, v65
	v_max3_f32 v237, v237, v66, v67
	s_waitcnt lgkmcnt(2)
	v_mfma_f32_32x32x16_bf16 v[32:47], v[242:245], v[246:249], v[32:47]
	ds_read_b128 v[242:245], v196 offset:6752
	v_max3_f32 v237, v237, v68, v69
	v_max3_f32 v237, v237, v70, v71
	s_waitcnt lgkmcnt(1)
	v_mfma_f32_32x32x16_bf16 v[48:63], v[238:241], v[250:253], v[48:63]
	v_max3_f32 v196, v237, v72, v73
	v_max3_f32 v196, v196, v74, v75
	s_waitcnt lgkmcnt(0)
	v_mfma_f32_32x32x16_bf16 v[32:47], v[242:245], v[250:253], v[32:47]
	v_max3_f32 v196, v196, v76, v77
	v_max3_f32 v196, v196, v78, v79
	v_mov_b32_e32 v237, v196
	v_mov_b32_e32 v238, v196
	s_nop 1
	v_permlane32_swap_b32_e32 v237, v238
	v_cndmask_b32_e64 v237, v237, v238, s[36:37]
	v_max_f32_e32 v237, v237, v237
	v_max_f32_e32 v196, v196, v237
	v_add_f32_e32 v237, 0x40c00000, v236
	v_cmp_gt_f32_e32 vcc, v196, v237
	s_nop 1
	v_cndmask_b32_e32 v196, v236, v196, vcc
	v_sub_f32_e32 v237, v236, v196
	v_exp_f32_e32 v237, v237
	v_cmp_neq_f32_e32 vcc, v196, v236
	s_cbranch_vccz .LBB0_353
	s_and_saveexec_b64 vcc, s[36:37]
	ds_write_b32 v176, v237 offset:58112
	s_or_b64 exec, exec, vcc
	v_add_u32_e32 v236, s75, v108
	ds_read_b128 v[238:241], v236 offset:58208
	ds_read_b128 v[242:245], v236 offset:58176
	ds_read_b128 v[246:249], v236 offset:58144
	ds_read_b128 v[250:253], v236 offset:58112
	s_waitcnt lgkmcnt(3)
	v_pk_mul_f32 v[12:13], v[12:13], v[238:239]
	s_waitcnt lgkmcnt(2)
	v_pk_mul_f32 v[8:9], v[8:9], v[242:243]
	s_waitcnt lgkmcnt(1)
	v_pk_mul_f32 v[4:5], v[4:5], v[246:247]
	v_pk_mul_f32 v[14:15], v[14:15], v[240:241]
	v_pk_mul_f32 v[10:11], v[10:11], v[244:245]
	v_pk_mul_f32 v[6:7], v[6:7], v[248:249]
	s_waitcnt lgkmcnt(0)
	v_pk_mul_f32 v[2:3], v[2:3], v[252:253]
	v_pk_mul_f32 v[0:1], v[0:1], v[250:251]
	v_pk_mul_f32 v[28:29], v[28:29], v[238:239]
	v_pk_mul_f32 v[24:25], v[24:25], v[242:243]
	v_pk_mul_f32 v[20:21], v[20:21], v[246:247]
	v_pk_mul_f32 v[30:31], v[30:31], v[240:241]
	v_pk_mul_f32 v[26:27], v[26:27], v[244:245]
	v_pk_mul_f32 v[22:23], v[22:23], v[248:249]
	v_pk_mul_f32 v[18:19], v[18:19], v[252:253]
	v_pk_mul_f32 v[16:17], v[16:17], v[250:251]
